# 22 of 32 exps per tile moved into own PV MFMA gaps
# baseline (speedup 1.0000x reference)
; DI void diff_core(unsigned char* smem, const u16* qptr, const u16* kbase, const u16* vtbase, int vld,
;                   int ntb, int ntw, int nvalid, int ks0, const float* lut, int qpos, bool active, bool grpB,
;                   f32x16 (&O)[4], float& l_out) {
;     ...
;     float mx = S[0][0];
; #pragma unroll
;     for (int kb = 0; kb < 2; ++kb)
; #pragma unroll
;       for (int i = 0; i < 16; ++i) mx = fmaxf(mx, S[kb][i]);
;     {
;       const unsigned um = __float_as_uint(mx);
;       const auto sw = __builtin_amdgcn_permlane32_swap(um, um, false, false);
;       mx = fmaxf(__uint_as_float(sw[0]), __uint_as_float(sw[1]));
;     }
;     if (t == 0) {
;       m = mx;
; #pragma unroll
;       for (int kb = 0; kb < 2; ++kb)
; #pragma unroll
;         for (int i = 0; i < 16; ++i) S[kb][i] -= mx;
;     } else if (__any(mx > 8.f)) {
;       const float d = fmaxf(mx, 0.f);
;       const float alpha = __builtin_amdgcn_exp2f(-d);
;       m += d;
;       l *= alpha;
; #pragma unroll
;       for (int tt = 0; tt < 4; ++tt)
; #pragma unroll
;         for (int e = 0; e < 16; ++e) O[tt][e] *= alpha;
; #pragma unroll
;       for (int kb = 0; kb < 2; ++kb)
; #pragma unroll
;         for (int i = 0; i < 16; ++i) S[kb][i] -= d;
;     }
;     float ps = 0.f;
; #pragma unroll
;     for (int kb = 0; kb < 2; ++kb)
; #pragma unroll
;       for (int i = 0; i < 16; ++i) {
;         const float pe = __builtin_amdgcn_exp2f(S[kb][i]);
;         S[kb][i] = pe;
;         ps += pe;
;       }
;     l += ps;
; #pragma unroll
;     for (int kb = 0; kb < 2; ++kb)
; #pragma unroll
;       for (int s2 = 0; s2 < 2; ++s2) {
;         u32x4 pk;
;         pk.x = pack2(S[kb][8 * s2 + 0], S[kb][8 * s2 + 1]);
;         pk.y = pack2(S[kb][8 * s2 + 2], S[kb][8 * s2 + 3]);
;         pk.z = pack2(S[kb][8 * s2 + 4], S[kb][8 * s2 + 5]);
;         pk.w = pack2(S[kb][8 * s2 + 6], S[kb][8 * s2 + 7]);
;         P[kb * 2 + s2] = pk;
;       }
.LBB0_357:
	v_max_f32_e32 v32, v1, v1
	v_max_f32_e32 v33, v0, v0
	v_max_f32_e32 v32, v33, v32
	v_max3_f32 v32, v32, v2, v3
	v_max3_f32 v32, v32, v4, v5
	v_max3_f32 v32, v32, v6, v7
	v_max3_f32 v32, v32, v8, v9
	v_max3_f32 v32, v32, v10, v11
	v_max3_f32 v32, v32, v12, v13
	v_max3_f32 v32, v32, v14, v15
	v_max3_f32 v32, v32, v16, v17
	v_max3_f32 v32, v32, v18, v19
	v_max3_f32 v32, v32, v20, v21
	v_max3_f32 v32, v32, v22, v23
	v_max3_f32 v32, v32, v24, v25
	v_max3_f32 v32, v32, v26, v27
	v_max3_f32 v32, v32, v28, v29
	v_max3_f32 v32, v32, v30, v31
	v_mov_b32_e32 v33, v32
	s_nop 1
	v_permlane32_swap_b32_e32 v32, v33
	v_max_f32_e32 v33, v33, v33
	v_max_f32_e32 v32, v32, v32
	v_max_f32_e32 v191, v32, v33
	v_xor_b32_e32 v232, 0x80000000, v191
	v_mov_b32_e32 v233, v232
	v_mov_b32_e32 v234, v232
	v_mov_b32_e32 v235, v232
	v_mov_b32_e32 v236, v232
	v_mov_b32_e32 v237, v232
	v_mov_b32_e32 v238, v232
	v_mov_b32_e32 v239, v232
	v_mov_b32_e32 v240, v232
	v_mov_b32_e32 v241, v232
	v_mov_b32_e32 v242, v232
	v_mov_b32_e32 v243, v232
	v_mov_b32_e32 v244, v232
	v_mov_b32_e32 v245, v232
	v_mov_b32_e32 v246, v232
	v_mov_b32_e32 v247, v232
	v_sub_f32_e32 v0, v0, v191
	v_sub_f32_e32 v1, v1, v191
	v_exp_f32_e32 v96, v0
	v_sub_f32_e32 v2, v2, v191
	v_exp_f32_e32 v97, v1
	v_sub_f32_e32 v3, v3, v191
	v_exp_f32_e32 v98, v2
	v_sub_f32_e32 v4, v4, v191
	v_exp_f32_e32 v99, v3
	v_sub_f32_e32 v5, v5, v191
	v_exp_f32_e32 v100, v4
	v_sub_f32_e32 v6, v6, v191
	v_exp_f32_e32 v101, v5
	v_sub_f32_e32 v7, v7, v191
	v_exp_f32_e32 v102, v6
	v_sub_f32_e32 v8, v8, v191
	v_exp_f32_e32 v103, v7
	v_sub_f32_e32 v9, v9, v191
	v_exp_f32_e32 v104, v8
	v_sub_f32_e32 v10, v10, v191
	v_exp_f32_e32 v105, v9
	v_sub_f32_e32 v11, v11, v191
	v_mov_b32_e32 v106, v10
	v_sub_f32_e32 v12, v12, v191
	v_mov_b32_e32 v107, v11
	v_sub_f32_e32 v13, v13, v191
	v_mov_b32_e32 v108, v12
	v_sub_f32_e32 v14, v14, v191
	v_mov_b32_e32 v109, v13
	v_sub_f32_e32 v15, v15, v191
	v_mov_b32_e32 v110, v14
	v_sub_f32_e32 v16, v16, v191
	v_mov_b32_e32 v111, v15
	v_sub_f32_e32 v17, v17, v191
	v_mov_b32_e32 v112, v16
	v_sub_f32_e32 v18, v18, v191
	v_mov_b32_e32 v113, v17
	v_sub_f32_e32 v19, v19, v191
	v_mov_b32_e32 v114, v18
	v_sub_f32_e32 v20, v20, v191
	v_mov_b32_e32 v115, v19
	v_sub_f32_e32 v21, v21, v191
	v_mov_b32_e32 v116, v20
	v_sub_f32_e32 v22, v22, v191
	v_mov_b32_e32 v117, v21
	v_sub_f32_e32 v23, v23, v191
	v_mov_b32_e32 v118, v22
	v_sub_f32_e32 v24, v24, v191
	v_mov_b32_e32 v119, v23
	v_sub_f32_e32 v25, v25, v191
	v_mov_b32_e32 v120, v24
	v_sub_f32_e32 v26, v26, v191
	v_mov_b32_e32 v121, v25
	v_sub_f32_e32 v27, v27, v191
	v_mov_b32_e32 v122, v26
	v_sub_f32_e32 v28, v28, v191
	v_mov_b32_e32 v123, v27
	v_sub_f32_e32 v29, v29, v191
	v_mov_b32_e32 v124, v28
	v_sub_f32_e32 v30, v30, v191
	v_mov_b32_e32 v125, v29
	v_sub_f32_e32 v31, v31, v191
	v_mov_b32_e32 v126, v30
	v_mov_b32_e32 v127, v31
	s_lshl_b32 s0, s62, 1
	s_sub_i32 s63, 0, s0
	s_lshl_b32 s0, s59, 10
	s_lshl_b32 s1, s62, 9
	s_add_i32 s0, s0, s1
	v_mov_b32_e32 v181, 0
	v_or_b32_e32 v0, s0, v183
	v_lshlrev_b32_e32 v1, 2, v182
	v_sub_u32_e32 v0, v0, v1
	s_lshl_b32 s0, s39, 7
	v_subrev_u32_e32 v0, s0, v0
	v_mov_b32_e32 v14, v163
	v_mov_b32_e32 v15, v163
	v_add_u32_e32 v199, s38, v0
	v_mov_b32_e32 v0, v163
	v_mov_b32_e32 v1, v163
	v_mov_b32_e32 v2, v163
	v_mov_b32_e32 v3, v163
	v_mov_b32_e32 v4, v163
	v_mov_b32_e32 v5, v163
	v_mov_b32_e32 v6, v163
	v_mov_b32_e32 v7, v163
	v_mov_b32_e32 v8, v163
	v_mov_b32_e32 v9, v163
	v_mov_b32_e32 v10, v163
	v_mov_b32_e32 v11, v163
	v_mov_b32_e32 v12, v163
	v_mov_b32_e32 v13, v163
	v_mov_b64_e32 v[30:31], v[14:15]
	v_mov_b64_e32 v[46:47], v[14:15]
	v_mov_b64_e32 v[62:63], v[14:15]
	v_add_u32_e32 v195, v188, v184
	v_add_u32_e32 v196, v187, v184
	v_add_u32_e32 v197, v186, v184
	v_add_u32_e32 v198, v185, v184
	s_movk_i32 s64, 0xff00
	s_mov_b32 s65, 0x20000
	v_mov_b64_e32 v[28:29], v[12:13]
	v_mov_b64_e32 v[26:27], v[10:11]
	v_mov_b64_e32 v[24:25], v[8:9]
	v_mov_b64_e32 v[22:23], v[6:7]
	v_mov_b64_e32 v[20:21], v[4:5]
	v_mov_b64_e32 v[18:19], v[2:3]
	v_mov_b64_e32 v[16:17], v[0:1]
	v_mov_b64_e32 v[44:45], v[12:13]
	v_mov_b64_e32 v[42:43], v[10:11]
	v_mov_b64_e32 v[40:41], v[8:9]
	v_mov_b64_e32 v[38:39], v[6:7]
	v_mov_b64_e32 v[36:37], v[4:5]
	v_mov_b64_e32 v[34:35], v[2:3]
	v_mov_b64_e32 v[32:33], v[0:1]
	v_mov_b64_e32 v[60:61], v[12:13]
	v_mov_b64_e32 v[58:59], v[10:11]
	v_mov_b64_e32 v[56:57], v[8:9]
	v_mov_b64_e32 v[54:55], v[6:7]
	v_mov_b64_e32 v[52:53], v[4:5]
	v_mov_b64_e32 v[50:51], v[2:3]
	v_mov_b64_e32 v[48:49], v[0:1]
	s_mov_b32 s0, 0
	v_add_u32_e32 v248, s0, v195
	ds_read_b128 v[200:203], v248 offset:16384
	ds_read_b128 v[204:207], v248 offset:20480
	ds_read_b128 v[208:211], v248 offset:24576
	ds_read_b128 v[212:215], v248 offset:28672
	v_add_u32_e32 v249, s0, v196
	ds_read_b128 v[216:219], v249 offset:16384
	ds_read_b128 v[220:223], v249 offset:20480
	ds_read_b128 v[224:227], v249 offset:24576
	ds_read_b128 v[228:231], v249 offset:28672
	s_branch .LBB0_360
.LBB0_358:
	v_exp_f32_e32 v96, v96
	v_exp_f32_e32 v97, v97
	v_exp_f32_e32 v98, v98
	v_exp_f32_e32 v99, v99
	v_exp_f32_e32 v100, v100
	v_exp_f32_e32 v101, v101
	v_exp_f32_e32 v102, v102
	v_exp_f32_e32 v103, v103
	v_exp_f32_e32 v104, v104
	v_exp_f32_e32 v105, v105
	s_add_i32 s0, s65, 0x8000
	s_and_b32 s0, s0, 0x18000
	v_add_u32_e32 v248, s0, v195
	ds_read_b128 v[200:203], v248 offset:16384
	ds_read_b128 v[204:207], v248 offset:20480
	ds_read_b128 v[208:211], v248 offset:24576
	ds_read_b128 v[212:215], v248 offset:28672
	v_add_u32_e32 v249, s0, v196
	ds_read_b128 v[216:219], v249 offset:16384
	ds_read_b128 v[220:223], v249 offset:20480
	ds_read_b128 v[224:227], v249 offset:24576
	ds_read_b128 v[228:231], v249 offset:28672

; DI void diff_core(unsigned char* smem, const u16* qptr, const u16* kbase, const u16* vtbase, int vld,
;                   int ntb, int ntw, int nvalid, int ks0, const float* lut, int qpos, bool active, bool grpB,
;                   f32x16 (&O)[4], float& l_out) {
;     ...
;   auto pv = [&](int slot) {
;     if (grpB) __builtin_amdgcn_s_setprio(2); else __builtin_amdgcn_s_setprio(1);
;     const LAS unsigned char* b = lds + slot * D_SLOT;
;     bf16x8 va[4], vb[4];
; #pragma unroll
;     for (int tt = 0; tt < 4; ++tt) va[tt] = *reinterpret_cast<const LAS bf16x8*>(b + voff[0] + tt * 32 * 128);
; #pragma unroll
;     for (int tt = 0; tt < 4; ++tt) vb[tt] = *reinterpret_cast<const LAS bf16x8*>(b + voff[1] + tt * 32 * 128);
;     {
;       const bf16x8 pf = __builtin_bit_cast(bf16x8, P[0]);
; #pragma unroll
;       for (int tt = 0; tt < 4; ++tt) O[tt] = MFMA(va[tt], pf, O[tt]);
;     }
; #pragma unroll
;     for (int tt = 0; tt < 4; ++tt) va[tt] = *reinterpret_cast<const LAS bf16x8*>(b + voff[2] + tt * 32 * 128);
;     {
;       const bf16x8 pf = __builtin_bit_cast(bf16x8, P[1]);
; #pragma unroll
;       for (int tt = 0; tt < 4; ++tt) O[tt] = MFMA(vb[tt], pf, O[tt]);
;     }
; #pragma unroll
;     for (int tt = 0; tt < 4; ++tt) vb[tt] = *reinterpret_cast<const LAS bf16x8*>(b + voff[3] + tt * 32 * 128);
;     {
;       const bf16x8 pf = __builtin_bit_cast(bf16x8, P[2]);
; #pragma unroll
;       for (int tt = 0; tt < 4; ++tt) O[tt] = MFMA(va[tt], pf, O[tt]);
;     }
;     {
;       const bf16x8 pf = __builtin_bit_cast(bf16x8, P[3]);
; #pragma unroll
;       for (int tt = 0; tt < 4; ++tt) O[tt] = MFMA(vb[tt], pf, O[tt]);
;     }
;     __builtin_amdgcn_sched_group_barrier(0x100, 8, 0);
;     __builtin_amdgcn_sched_group_barrier(0x008, 4, 0);
;     __builtin_amdgcn_sched_group_barrier(0x100, 4, 0);
;     __builtin_amdgcn_sched_group_barrier(0x008, 4, 0);
;     __builtin_amdgcn_sched_group_barrier(0x100, 4, 0);
;     __builtin_amdgcn_sched_group_barrier(0x008, 8, 0);
;     __builtin_amdgcn_s_setprio(0);
;   };
;     ...
;     float ps = 0.f;
; #pragma unroll
;     for (int kb = 0; kb < 2; ++kb)
; #pragma unroll
;       for (int i = 0; i < 16; ++i) {
;         const float pe = __builtin_amdgcn_exp2f(S[kb][i]);
;         S[kb][i] = pe;
;         ps += pe;
;       }
;     l += ps;
; #pragma unroll
;     for (int kb = 0; kb < 2; ++kb)
; #pragma unroll
.LBB0_360:
	s_add_i32 s66, s64, 0x101
	s_cmp_gt_u32 s66, s16
	s_cbranch_scc1 .LBB0_362
	s_setprio 2
	s_and_b32 s0, s65, 0x18000
	v_add_u32_e32 v248, s0, v197
	ds_read_b128 v[64:67], v248 offset:16384
	ds_read_b128 v[68:71], v248 offset:20480
	ds_read_b128 v[72:75], v248 offset:24576
	ds_read_b128 v[76:79], v248 offset:28672
	s_add_i32 s67, s65, 0xfffe8000
	s_and_b32 s67, s67, 0x18000
	v_cvt_pk_bf16_f32 v144, v96, v97
	v_cvt_pk_bf16_f32 v145, v98, v99
	v_cvt_pk_bf16_f32 v146, v100, v101
	v_cvt_pk_bf16_f32 v147, v102, v103
	v_add_f32_e32 v250, v97, v96
	v_add_f32_e32 v250, v98, v250
	v_add_f32_e32 v250, v99, v250
	s_waitcnt lgkmcnt(4)
	v_mfma_f32_32x32x16_bf16 v[48:63], v[200:203], v[144:147], v[48:63]
	v_cvt_pk_bf16_f32 v148, v104, v105
	v_exp_f32_e32 v106, v106
	v_exp_f32_e32 v107, v107
	v_add_f32_e32 v250, v100, v250
	v_add_f32_e32 v250, v101, v250
	v_add_u32_e32 v249, s0, v198
	ds_read_b128 v[80:83], v249 offset:16384
	ds_read_b128 v[84:87], v249 offset:20480
	ds_read_b128 v[88:91], v249 offset:24576
	ds_read_b128 v[92:95], v249 offset:28672
	v_mfma_f32_32x32x16_bf16 v[32:47], v[204:207], v[144:147], v[32:47]
	v_cvt_pk_bf16_f32 v149, v106, v107
	v_exp_f32_e32 v108, v108
	v_exp_f32_e32 v109, v109
	v_add_f32_e32 v250, v102, v250
	v_add_f32_e32 v250, v103, v250
	v_mfma_f32_32x32x16_bf16 v[16:31], v[208:211], v[144:147], v[16:31]
	v_cvt_pk_bf16_f32 v150, v108, v109
	v_exp_f32_e32 v110, v110
	v_exp_f32_e32 v111, v111
	v_add_f32_e32 v250, v104, v250
	v_add_f32_e32 v250, v105, v250
	v_mfma_f32_32x32x16_bf16 v[0:15], v[212:215], v[144:147], v[0:15]
	v_cvt_pk_bf16_f32 v151, v110, v111
	v_exp_f32_e32 v112, v112
	v_exp_f32_e32 v113, v113
	v_add_f32_e32 v250, v106, v250
	v_add_f32_e32 v250, v107, v250
	v_mfma_f32_32x32x16_bf16 v[48:63], v[216:219], v[148:151], v[48:63]
	v_cvt_pk_bf16_f32 v152, v112, v113
	v_exp_f32_e32 v114, v114
	v_exp_f32_e32 v115, v115
	v_add_f32_e32 v250, v108, v250
	v_add_f32_e32 v250, v109, v250
	v_mfma_f32_32x32x16_bf16 v[32:47], v[220:223], v[148:151], v[32:47]
	v_cvt_pk_bf16_f32 v153, v114, v115
	v_exp_f32_e32 v116, v116
	v_exp_f32_e32 v117, v117
	v_add_f32_e32 v250, v110, v250
	v_add_f32_e32 v250, v111, v250
	v_mfma_f32_32x32x16_bf16 v[16:31], v[224:227], v[148:151], v[16:31]
	v_cvt_pk_bf16_f32 v154, v116, v117
	v_exp_f32_e32 v118, v118
	v_exp_f32_e32 v119, v119
	v_add_f32_e32 v250, v112, v250
	v_add_f32_e32 v250, v113, v250
	v_mfma_f32_32x32x16_bf16 v[0:15], v[228:231], v[148:151], v[0:15]
	v_cvt_pk_bf16_f32 v155, v118, v119
	v_exp_f32_e32 v120, v120
	v_exp_f32_e32 v121, v121
	v_add_f32_e32 v250, v114, v250
	v_add_f32_e32 v250, v115, v250
	v_add_u32_e32 v248, s67, v177
	ds_read_b128 v[200:203], v248
	ds_read_b128 v[204:207], v248 offset:8192
	v_add_u32_e32 v249, s67, v178
	ds_read_b128 v[208:211], v249
	ds_read_b128 v[212:215], v249 offset:8192
	s_waitcnt lgkmcnt(8)
	v_mfma_f32_32x32x16_bf16 v[48:63], v[64:67], v[152:155], v[48:63]
	v_cvt_pk_bf16_f32 v156, v120, v121
	v_exp_f32_e32 v122, v122
	v_exp_f32_e32 v123, v123
	v_add_f32_e32 v250, v116, v250
	v_add_f32_e32 v250, v117, v250
	v_mfma_f32_32x32x16_bf16 v[32:47], v[68:71], v[152:155], v[32:47]
	v_cvt_pk_bf16_f32 v157, v122, v123
	v_exp_f32_e32 v124, v124
	v_exp_f32_e32 v125, v125
	v_add_f32_e32 v250, v118, v250
	v_add_f32_e32 v250, v119, v250
	v_mfma_f32_32x32x16_bf16 v[16:31], v[72:75], v[152:155], v[16:31]
	v_cvt_pk_bf16_f32 v158, v124, v125
	v_exp_f32_e32 v126, v126
	v_exp_f32_e32 v127, v127
	v_add_f32_e32 v250, v120, v250
	v_add_f32_e32 v250, v121, v250
	v_mfma_f32_32x32x16_bf16 v[0:15], v[76:79], v[152:155], v[0:15]
	v_cvt_pk_bf16_f32 v159, v126, v127
	v_add_f32_e32 v250, v122, v250
	v_add_f32_e32 v250, v123, v250
	v_add_u32_e32 v248, s67, v179
	ds_read_b128 v[216:219], v248
	ds_read_b128 v[220:223], v248 offset:8192
	v_add_u32_e32 v249, s67, v180
	ds_read_b128 v[224:227], v249
	ds_read_b128 v[228:231], v249 offset:8192
	s_waitcnt lgkmcnt(8)
	v_mfma_f32_32x32x16_bf16 v[48:63], v[80:83], v[156:159], v[48:63]
	v_add_f32_e32 v250, v124, v250
	v_add_f32_e32 v250, v125, v250
	v_mfma_f32_32x32x16_bf16 v[32:47], v[84:87], v[156:159], v[32:47]
	v_add_f32_e32 v250, v126, v250
	v_add_f32_e32 v250, v127, v250
	v_mfma_f32_32x32x16_bf16 v[16:31], v[88:91], v[156:159], v[16:31]
	v_mfma_f32_32x32x16_bf16 v[0:15], v[92:95], v[156:159], v[0:15]
	v_add_f32_e32 v181, v181, v250
	s_setprio 0

; #define D_BAR do { asm volatile("" ::: "memory"); __builtin_amdgcn_s_barrier(); asm volatile("" ::: "memory"); } while (0)
; DI void diff_core(unsigned char* smem, const u16* qptr, const u16* kbase, const u16* vtbase, int vld,
;                   int ntb, int ntw, int nvalid, int ks0, const float* lut, int qpos, bool active, bool grpB,
;                   f32x16 (&O)[4], float& l_out) {
;     ...
;     float ps = 0.f;
; #pragma unroll
;     for (int kb = 0; kb < 2; ++kb)
; #pragma unroll
;       for (int i = 0; i < 16; ++i) {
;         const float pe = __builtin_amdgcn_exp2f(S[kb][i]);
;         S[kb][i] = pe;
;         ps += pe;
;       }
;     l += ps;
; #pragma unroll
;     for (int kb = 0; kb < 2; ++kb)
; #pragma unroll
;       for (int s2 = 0; s2 < 2; ++s2) {
;         u32x4 pk;
;         pk.x = pack2(S[kb][8 * s2 + 0], S[kb][8 * s2 + 1]);
;         pk.y = pack2(S[kb][8 * s2 + 2], S[kb][8 * s2 + 3]);
;         pk.z = pack2(S[kb][8 * s2 + 4], S[kb][8 * s2 + 5]);
;         pk.w = pack2(S[kb][8 * s2 + 6], S[kb][8 * s2 + 7]);
;         P[kb * 2 + s2] = pk;
;       }
;     ...
;       if (act_t) softmax(t);
;       asm volatile("s_waitcnt vmcnt(4)" ::: "memory");
;       D_BAR;
;       if (act_t) pv(t & 3);
;       __builtin_amdgcn_sched_barrier(0);
;       if (active && (t + 1) < ntw) qk((t + 1) & 3);
.LBB0_383:
	v_exp_f32_e32 v80, v80
	v_exp_f32_e32 v81, v81
	v_exp_f32_e32 v82, v82
	v_exp_f32_e32 v83, v83
	v_exp_f32_e32 v84, v84
	v_exp_f32_e32 v85, v85
	v_exp_f32_e32 v86, v86
	v_exp_f32_e32 v87, v87
	v_exp_f32_e32 v88, v88
	v_exp_f32_e32 v89, v89
	v_cvt_pk_bf16_f32 v144, v80, v81
	v_cvt_pk_bf16_f32 v145, v82, v83
	v_cvt_pk_bf16_f32 v146, v84, v85
	v_cvt_pk_bf16_f32 v147, v86, v87
	v_add_f32_e32 v250, v81, v80
	v_add_f32_e32 v250, v82, v250
	v_add_f32_e32 v250, v83, v250
.LBB0_384:
	s_waitcnt vmcnt(4)
	s_barrier
	s_andn2_b64 vcc, exec, s[0:1]
	s_cbranch_vccnz .LBB0_386
	s_setprio 2
	s_waitcnt lgkmcnt(0)
	v_mfma_f32_32x32x16_bf16 v[48:63], v[200:203], v[144:147], v[48:63]
	v_cvt_pk_bf16_f32 v148, v88, v89
	v_exp_f32_e32 v90, v90
	v_exp_f32_e32 v91, v91
	v_add_f32_e32 v250, v84, v250
	v_add_f32_e32 v250, v85, v250
	v_add_u32_e32 v97, s100, v186
	ds_read_b128 v[98:101], v97 offset:16384
	ds_read_b128 v[102:105], v97 offset:20480
	ds_read_b128 v[106:109], v97 offset:24576
	ds_read_b128 v[110:113], v97 offset:28672
	v_mfma_f32_32x32x16_bf16 v[32:47], v[204:207], v[144:147], v[32:47]
	v_cvt_pk_bf16_f32 v149, v90, v91
	v_exp_f32_e32 v92, v92
	v_exp_f32_e32 v93, v93
	v_add_f32_e32 v250, v86, v250
	v_add_f32_e32 v250, v87, v250
	v_add_u32_e32 v126, s100, v184
	ds_read_b128 v[114:117], v126 offset:16384
	ds_read_b128 v[118:121], v126 offset:20480
	ds_read_b128 v[122:125], v126 offset:24576
	ds_read_b128 v[196:199], v126 offset:28672
	v_mfma_f32_32x32x16_bf16 v[16:31], v[208:211], v[144:147], v[16:31]
	v_cvt_pk_bf16_f32 v150, v92, v93
	v_exp_f32_e32 v94, v94
	v_exp_f32_e32 v95, v95
	v_add_f32_e32 v250, v88, v250
	v_add_f32_e32 v250, v89, v250
	v_mfma_f32_32x32x16_bf16 v[0:15], v[212:215], v[144:147], v[0:15]
	v_cvt_pk_bf16_f32 v151, v94, v95
	v_exp_f32_e32 v64, v64
	v_exp_f32_e32 v65, v65
	v_add_f32_e32 v250, v90, v250
	v_add_f32_e32 v250, v91, v250
	v_mfma_f32_32x32x16_bf16 v[48:63], v[216:219], v[148:151], v[48:63]
	v_cvt_pk_bf16_f32 v152, v64, v65
	v_exp_f32_e32 v66, v66
	v_exp_f32_e32 v67, v67
	v_add_f32_e32 v250, v92, v250
	v_add_f32_e32 v250, v93, v250
	v_mfma_f32_32x32x16_bf16 v[32:47], v[220:223], v[148:151], v[32:47]
	v_cvt_pk_bf16_f32 v153, v66, v67
	v_exp_f32_e32 v68, v68
	v_exp_f32_e32 v69, v69
	v_add_f32_e32 v250, v94, v250
	v_add_f32_e32 v250, v95, v250
	v_mfma_f32_32x32x16_bf16 v[16:31], v[224:227], v[148:151], v[16:31]
	v_cvt_pk_bf16_f32 v154, v68, v69
	v_exp_f32_e32 v70, v70
	v_exp_f32_e32 v71, v71
	v_add_f32_e32 v250, v64, v250
	v_add_f32_e32 v250, v65, v250
	v_mfma_f32_32x32x16_bf16 v[0:15], v[228:231], v[148:151], v[0:15]
	v_cvt_pk_bf16_f32 v155, v70, v71
	v_exp_f32_e32 v72, v72
	v_exp_f32_e32 v73, v73
	v_add_f32_e32 v250, v66, v250
	v_add_f32_e32 v250, v67, v250
	v_add_u32_e32 v97, s101, v177
	ds_read_b128 v[200:203], v97
	ds_read_b128 v[204:207], v97 offset:8192
	v_add_u32_e32 v126, s101, v178
	ds_read_b128 v[208:211], v126
	ds_read_b128 v[212:215], v126 offset:8192
	s_waitcnt lgkmcnt(8)
	v_mfma_f32_32x32x16_bf16 v[48:63], v[98:101], v[152:155], v[48:63]
	v_cvt_pk_bf16_f32 v156, v72, v73
	v_exp_f32_e32 v74, v74
	v_exp_f32_e32 v75, v75
	v_add_f32_e32 v250, v68, v250
	v_add_f32_e32 v250, v69, v250
	v_mfma_f32_32x32x16_bf16 v[32:47], v[102:105], v[152:155], v[32:47]
	v_cvt_pk_bf16_f32 v157, v74, v75
	v_exp_f32_e32 v76, v76
	v_exp_f32_e32 v77, v77
	v_add_f32_e32 v250, v70, v250
	v_add_f32_e32 v250, v71, v250
	v_mfma_f32_32x32x16_bf16 v[16:31], v[106:109], v[152:155], v[16:31]
	v_cvt_pk_bf16_f32 v158, v76, v77
	v_exp_f32_e32 v78, v78
	v_exp_f32_e32 v79, v79
	v_add_f32_e32 v250, v72, v250
	v_add_f32_e32 v250, v73, v250
	v_mfma_f32_32x32x16_bf16 v[0:15], v[110:113], v[152:155], v[0:15]
	v_cvt_pk_bf16_f32 v159, v78, v79
	v_add_f32_e32 v250, v74, v250
	v_add_f32_e32 v250, v75, v250
	v_add_u32_e32 v97, s101, v179
	ds_read_b128 v[216:219], v97
	ds_read_b128 v[220:223], v97 offset:8192
	v_add_u32_e32 v126, s101, v180
	ds_read_b128 v[224:227], v126
	ds_read_b128 v[228:231], v126 offset:8192
	s_waitcnt lgkmcnt(8)
	v_mfma_f32_32x32x16_bf16 v[48:63], v[114:117], v[156:159], v[48:63]
	v_add_f32_e32 v250, v76, v250
	v_add_f32_e32 v250, v77, v250
	v_mfma_f32_32x32x16_bf16 v[32:47], v[118:121], v[156:159], v[32:47]
	v_add_f32_e32 v250, v78, v250
	v_add_f32_e32 v250, v79, v250
	v_mfma_f32_32x32x16_bf16 v[16:31], v[122:125], v[156:159], v[16:31]
	v_mfma_f32_32x32x16_bf16 v[0:15], v[196:199], v[156:159], v[0:15]
	v_add_f32_e32 v181, v181, v250
	s_setprio 0
